# grid barrier: all blocks poll the top-level arrival counter directly (no per-XCD release hop, no TOPGEN hop)
# speedup vs baseline: 1.0328x; 1.0250x over previous
; DI unsigned xb_ld(unsigned* p)              { return __hip_atomic_load(p, __ATOMIC_RELAXED, __HIP_MEMORY_SCOPE_AGENT); }
; DI unsigned xb_add(unsigned* p, unsigned v) { return __hip_atomic_fetch_add(p, v, __ATOMIC_RELAXED, __HIP_MEMORY_SCOPE_AGENT); }
; #define XB_SPIN(cond, bar) do { unsigned _sp = 0; while (cond) { __builtin_amdgcn_s_sleep(1); \
;     if ((++_sp & 255u) == 0u) { if (xb_ld(&(bar)[XB_TMO])) break; if (_sp > XB_SPIN_CAP) { atomicAdd(&(bar)[XB_TMO], 1u); break; } } } } while (0)
; DI void xcd_barrier(const XcdBarrier& b) {
;     ...
;     const unsigned old = xb_add(&bar[XB_XSUB(b.x)], 1u);
;     const unsigned gen = old / nloc;
;     if (old + 1u == (gen + 1u) * nloc) {
;       __builtin_amdgcn_fence(__ATOMIC_RELEASE, "agent");
;       asm volatile("s_waitcnt vmcnt(0)" ::: "memory");
;       const unsigned og = xb_add(&bar[XB_TOP], 1u);
;       const unsigned tg = og / nx;
;       if (og + 1u == (tg + 1u) * nx) xb_add(&bar[XB_TOPGEN], 1u);
;       else XB_SPIN(xb_ld(&bar[XB_TOPGEN]) == tg, bar);
;       __builtin_amdgcn_fence(__ATOMIC_ACQUIRE, "agent");
;       xb_add(&bar[XB_XGEN(b.x)], 1u);
;       asm volatile("s_waitcnt vmcnt(0)" ::: "memory");
;     } else {
;       XB_SPIN(xb_ld(&bar[XB_XGEN(b.x)]) == gen, bar);
.LBB0_2080:
	s_or_b64 exec, exec, s[30:31]
	v_cvt_f32_u32_e32 v5, v3
	s_waitcnt vmcnt(0)
	v_readfirstlane_b32 s28, v4
	v_sub_u32_e32 v4, 0, v3
	v_rcp_iflag_f32_e32 v5, v5
	v_add_u32_e32 v6, s28, v0
	v_mul_f32_e32 v5, 0x4f7ffffe, v5
	v_cvt_u32_f32_e32 v5, v5
	v_mul_lo_u32 v0, v4, v5
	v_mul_hi_u32 v0, v5, v0
	v_add_u32_e32 v0, v5, v0
	v_mul_hi_u32 v0, v6, v0
	v_mul_lo_u32 v4, v0, v3
	v_sub_u32_e32 v4, v6, v4
	v_add_u32_e32 v5, 1, v0
	v_cmp_ge_u32_e32 vcc, v4, v3
	s_nop 1
	v_cndmask_b32_e32 v0, v0, v5, vcc
	v_sub_u32_e32 v5, v4, v3
	v_cndmask_b32_e32 v4, v4, v5, vcc
	v_add_u32_e32 v5, 1, v0
	v_cmp_ge_u32_e32 vcc, v4, v3
	v_add_u32_e32 v4, 1, v6
	s_nop 0
	v_cndmask_b32_e32 v0, v0, v5, vcc
	v_mul_lo_u32 v5, v3, v0
	v_add_u32_e32 v3, v5, v3
	v_cmp_ne_u32_e32 vcc, v4, v3
	s_and_saveexec_b64 s[30:31], vcc
	s_xor_b64 s[30:31], exec, s[30:31]
	s_cbranch_execz .LBB0_2094
	v_readlane_b32 s4, v254, 60
	v_readlane_b32 s5, v254, 61
	s_waitcnt lgkmcnt(0)
	v_mad_u32_u24 v7, v0, v2, v2
	s_nop 2
	global_load_dword v2, v1, s[4:5] sc1
	s_waitcnt vmcnt(0)
	v_cmp_lt_u32_e32 vcc, v2, v7
	s_and_saveexec_b64 s[40:41], vcc
	s_cbranch_execz .LBB0_2093
	s_mov_b32 s28, 1
	s_mov_b64 s[42:43], 0
	s_branch .LBB0_2084

; DI unsigned xb_ld(unsigned* p)              { return __hip_atomic_load(p, __ATOMIC_RELAXED, __HIP_MEMORY_SCOPE_AGENT); }
; DI unsigned xb_add(unsigned* p, unsigned v) { return __hip_atomic_fetch_add(p, v, __ATOMIC_RELAXED, __HIP_MEMORY_SCOPE_AGENT); }
; #define XB_SPIN(cond, bar) do { unsigned _sp = 0; while (cond) { __builtin_amdgcn_s_sleep(1); \
;     if ((++_sp & 255u) == 0u) { if (xb_ld(&(bar)[XB_TMO])) break; if (_sp > XB_SPIN_CAP) { atomicAdd(&(bar)[XB_TMO], 1u); break; } } } } while (0)
; DI void xcd_barrier(const XcdBarrier& b) {
;     ...
;       else XB_SPIN(xb_ld(&bar[XB_TOPGEN]) == tg, bar);
;       __builtin_amdgcn_fence(__ATOMIC_ACQUIRE, "agent");
;       xb_add(&bar[XB_XGEN(b.x)], 1u);
;       asm volatile("s_waitcnt vmcnt(0)" ::: "memory");
;     } else {
;       XB_SPIN(xb_ld(&bar[XB_XGEN(b.x)]) == gen, bar);
.LBB0_2088:
	v_readlane_b32 s4, v254, 60
	v_readlane_b32 s5, v254, 61
	s_add_i32 s28, s28, 1
	s_mov_b64 s[48:49], -1
	s_nop 2
	global_load_dword v2, v1, s[4:5] sc1
	s_waitcnt vmcnt(0)
	v_cmp_ge_u32_e32 vcc, v2, v7
	s_orn2_b64 s[46:47], vcc, exec
	s_branch .LBB0_2083

; DI unsigned xb_ld(unsigned* p)              { return __hip_atomic_load(p, __ATOMIC_RELAXED, __HIP_MEMORY_SCOPE_AGENT); }
; DI unsigned xb_add(unsigned* p, unsigned v) { return __hip_atomic_fetch_add(p, v, __ATOMIC_RELAXED, __HIP_MEMORY_SCOPE_AGENT); }
; #define XB_SPIN(cond, bar) do { unsigned _sp = 0; while (cond) { __builtin_amdgcn_s_sleep(1); \
;     if ((++_sp & 255u) == 0u) { if (xb_ld(&(bar)[XB_TMO])) break; if (_sp > XB_SPIN_CAP) { atomicAdd(&(bar)[XB_TMO], 1u); break; } } } } while (0)
; DI void xcd_barrier(const XcdBarrier& b) {
;     ...
;       const unsigned og = xb_add(&bar[XB_TOP], 1u);
;       const unsigned tg = og / nx;
;       if (og + 1u == (tg + 1u) * nx) xb_add(&bar[XB_TOPGEN], 1u);
;       else XB_SPIN(xb_ld(&bar[XB_TOPGEN]) == tg, bar);
;       __builtin_amdgcn_fence(__ATOMIC_ACQUIRE, "agent");
;       xb_add(&bar[XB_XGEN(b.x)], 1u);
;       asm volatile("s_waitcnt vmcnt(0)" ::: "memory");
;     } else {
;       XB_SPIN(xb_ld(&bar[XB_XGEN(b.x)]) == gen, bar);
.LBB0_2097:
	s_or_b64 exec, exec, s[40:41]
	s_waitcnt vmcnt(0)
	v_readfirstlane_b32 s28, v3
	v_sub_u32_e32 v4, 0, v2
	v_readlane_b32 s4, v254, 62
	v_add_u32_e32 v3, s28, v0
	v_cvt_f32_u32_e32 v0, v2
	v_readlane_b32 s5, v254, 63
	s_mov_b64 s[40:41], -1
	v_rcp_iflag_f32_e32 v0, v0
	s_nop 0
	v_mul_f32_e32 v0, 0x4f7ffffe, v0
	v_cvt_u32_f32_e32 v0, v0
	v_mul_lo_u32 v4, v4, v0
	v_mul_hi_u32 v4, v0, v4
	v_add_u32_e32 v0, v0, v4
	v_mul_hi_u32 v0, v3, v0
	v_mul_lo_u32 v4, v0, v2
	v_sub_u32_e32 v4, v3, v4
	v_cmp_ge_u32_e32 vcc, v4, v2
	v_add_u32_e32 v5, 1, v0
	v_add_u32_e32 v3, 1, v3
	v_cndmask_b32_e32 v0, v0, v5, vcc
	v_sub_u32_e32 v5, v4, v2
	v_cndmask_b32_e32 v4, v4, v5, vcc
	v_cmp_ge_u32_e32 vcc, v4, v2
	v_add_u32_e32 v4, 1, v0
	s_nop 0
	v_cndmask_b32_e32 v0, v0, v4, vcc
	v_mul_lo_u32 v4, v2, v0
	v_add_u32_e32 v2, v4, v2
	v_mov_b32_e32 v7, v2
	v_cmp_ne_u32_e32 vcc, v3, v2
	v_mov_b64_e32 v[2:3], s[4:5]
	s_and_saveexec_b64 s[30:31], vcc
	s_cbranch_execz .LBB0_2109
	v_readlane_b32 s4, v254, 60
	v_readlane_b32 s5, v254, 61
	s_mov_b64 s[42:43], 0
	s_nop 3
	global_load_dword v2, v1, s[4:5] sc1
	s_waitcnt vmcnt(0)
	v_cmp_lt_u32_e32 vcc, v2, v7
	s_and_saveexec_b64 s[40:41], vcc
	s_cbranch_execz .LBB0_2108
	s_mov_b32 s28, 1
	s_branch .LBB0_2101
